# code placement: every 16-MFMA block of the gemm1 and gemm2 K-loops starts at 4 mod 8 (s_nop padding)
# baseline (speedup 1.0000x reference)
.LBB0_225:
	ds_read_b128 v[132:135], v142
	ds_read_b128 v[136:139], v142 offset:1024
	ds_read_b128 v[150:153], v142 offset:2048
	ds_read_b128 v[154:157], v142 offset:3072
	s_add_i32 s69, s8, s68
	s_add_i32 s70, s69, 0x80080
	s_mov_b32 m0, s7
	ds_read_b128 v[158:161], v143
	ds_read_b128 v[162:165], v143 offset:1024
	ds_read_b128 v[166:169], v144
	ds_read_b128 v[170:173], v144 offset:1024
	ds_read_b128 v[178:181], v145
	ds_read_b128 v[214:217], v145 offset:1024
	ds_read_b128 v[218:221], v146
	ds_read_b128 v[222:225], v146 offset:1024
	buffer_load_dwordx4 v140, s[48:51], s70 offen lds
	s_mov_b32 m0, s6
	s_nop 0
	buffer_load_dwordx4 v141, s[48:51], s70 offen lds
	s_waitcnt lgkmcnt(8)
	s_barrier
	s_waitcnt lgkmcnt(0)
	s_setprio 1
	s_waitcnt lgkmcnt(0)
	v_mfma_f32_16x16x32_bf16 v[126:129], v[132:135], v[158:161], v[126:129]
	v_mfma_f32_16x16x32_bf16 v[122:125], v[150:153], v[158:161], v[122:125]
	v_mfma_f32_16x16x32_bf16 v[118:121], v[132:135], v[166:169], v[118:121]
	v_mfma_f32_16x16x32_bf16 v[114:117], v[150:153], v[166:169], v[114:117]
	v_mfma_f32_16x16x32_bf16 v[110:113], v[132:135], v[178:181], v[110:113]
	v_mfma_f32_16x16x32_bf16 v[106:109], v[150:153], v[178:181], v[106:109]
	v_mfma_f32_16x16x32_bf16 v[102:105], v[132:135], v[218:221], v[102:105]
	v_mfma_f32_16x16x32_bf16 v[98:101], v[150:153], v[218:221], v[98:101]
	v_mfma_f32_16x16x32_bf16 v[126:129], v[136:139], v[162:165], v[126:129]
	v_mfma_f32_16x16x32_bf16 v[122:125], v[154:157], v[162:165], v[122:125]
	v_mfma_f32_16x16x32_bf16 v[118:121], v[136:139], v[170:173], v[118:121]
	v_mfma_f32_16x16x32_bf16 v[114:117], v[154:157], v[170:173], v[114:117]
	v_mfma_f32_16x16x32_bf16 v[110:113], v[136:139], v[214:217], v[110:113]
	v_mfma_f32_16x16x32_bf16 v[106:109], v[154:157], v[214:217], v[106:109]
	v_mfma_f32_16x16x32_bf16 v[102:105], v[136:139], v[222:225], v[102:105]
	v_mfma_f32_16x16x32_bf16 v[98:101], v[154:157], v[222:225], v[98:101]
	s_setprio 0
	s_barrier
	s_add_i32 s70, s9, s68
	s_add_i32 s71, s70, 0x100
	s_mov_b32 m0, s28
	ds_read_b128 v[226:229], v147
	ds_read_b128 v[230:233], v147 offset:1024
	ds_read_b128 v[234:237], v147 offset:2048
	ds_read_b128 v[238:241], v147 offset:3072
	buffer_load_dwordx4 v140, s[44:47], s71 offen lds
	s_mov_b32 m0, s29
	s_nop 0
	buffer_load_dwordx4 v141, s[44:47], s71 offen lds
	s_barrier
	s_waitcnt lgkmcnt(0)
	s_setprio 1
	s_waitcnt lgkmcnt(0)
	v_mfma_f32_16x16x32_bf16 v[94:97], v[226:229], v[158:161], v[94:97]
	v_mfma_f32_16x16x32_bf16 v[90:93], v[234:237], v[158:161], v[90:93]
	v_mfma_f32_16x16x32_bf16 v[86:89], v[226:229], v[166:169], v[86:89]
	v_mfma_f32_16x16x32_bf16 v[82:85], v[234:237], v[166:169], v[82:85]
	v_mfma_f32_16x16x32_bf16 v[78:81], v[226:229], v[178:181], v[78:81]
	v_mfma_f32_16x16x32_bf16 v[74:77], v[234:237], v[178:181], v[74:77]
	v_mfma_f32_16x16x32_bf16 v[70:73], v[226:229], v[218:221], v[70:73]
	v_mfma_f32_16x16x32_bf16 v[66:69], v[234:237], v[218:221], v[66:69]
	v_mfma_f32_16x16x32_bf16 v[94:97], v[230:233], v[162:165], v[94:97]
	v_mfma_f32_16x16x32_bf16 v[90:93], v[238:241], v[162:165], v[90:93]
	v_mfma_f32_16x16x32_bf16 v[86:89], v[230:233], v[170:173], v[86:89]
	v_mfma_f32_16x16x32_bf16 v[82:85], v[238:241], v[170:173], v[82:85]
	v_mfma_f32_16x16x32_bf16 v[78:81], v[230:233], v[214:217], v[78:81]
	v_mfma_f32_16x16x32_bf16 v[74:77], v[238:241], v[214:217], v[74:77]
	v_mfma_f32_16x16x32_bf16 v[70:73], v[230:233], v[222:225], v[70:73]
	v_mfma_f32_16x16x32_bf16 v[66:69], v[238:241], v[222:225], v[66:69]
	s_setprio 0
	s_add_i32 s71, s69, 0x100
	s_mov_b32 m0, s27
	s_barrier
	ds_read_b128 v[158:161], v143 offset:16384
	ds_read_b128 v[162:165], v143 offset:17408
	ds_read_b128 v[166:169], v144 offset:16384
	ds_read_b128 v[170:173], v144 offset:17408
	ds_read_b128 v[178:181], v145 offset:16384
	ds_read_b128 v[214:217], v145 offset:17408
	ds_read_b128 v[218:221], v146 offset:16384
	ds_read_b128 v[222:225], v146 offset:17408
	buffer_load_dwordx4 v140, s[48:51], s71 offen lds
	s_mov_b32 m0, s30
	s_nop 0
	buffer_load_dwordx4 v141, s[48:51], s71 offen lds
	s_barrier
	s_waitcnt lgkmcnt(0)
	s_setprio 1
	s_waitcnt lgkmcnt(0)
	s_nop 0
	v_mfma_f32_16x16x32_bf16 v[62:65], v[132:135], v[158:161], v[62:65]
	v_mfma_f32_16x16x32_bf16 v[58:61], v[150:153], v[158:161], v[58:61]
	v_mfma_f32_16x16x32_bf16 v[54:57], v[132:135], v[166:169], v[54:57]
	v_mfma_f32_16x16x32_bf16 v[50:53], v[150:153], v[166:169], v[50:53]
	v_mfma_f32_16x16x32_bf16 v[46:49], v[132:135], v[178:181], v[46:49]
	v_mfma_f32_16x16x32_bf16 v[42:45], v[150:153], v[178:181], v[42:45]
	v_mfma_f32_16x16x32_bf16 v[38:41], v[132:135], v[218:221], v[38:41]
	v_mfma_f32_16x16x32_bf16 v[34:37], v[150:153], v[218:221], v[34:37]
	v_mfma_f32_16x16x32_bf16 v[62:65], v[136:139], v[162:165], v[62:65]
	v_mfma_f32_16x16x32_bf16 v[58:61], v[154:157], v[162:165], v[58:61]
	v_mfma_f32_16x16x32_bf16 v[54:57], v[136:139], v[170:173], v[54:57]
	v_mfma_f32_16x16x32_bf16 v[50:53], v[154:157], v[170:173], v[50:53]
	v_mfma_f32_16x16x32_bf16 v[46:49], v[136:139], v[214:217], v[46:49]
	v_mfma_f32_16x16x32_bf16 v[42:45], v[154:157], v[214:217], v[42:45]
	v_mfma_f32_16x16x32_bf16 v[38:41], v[136:139], v[222:225], v[38:41]
	v_mfma_f32_16x16x32_bf16 v[34:37], v[154:157], v[222:225], v[34:37]
	s_setprio 0
	s_barrier
	s_add_i32 s71, s70, 0x80100
	s_mov_b32 m0, s31
	s_nop 0
	buffer_load_dwordx4 v140, s[44:47], s71 offen lds
	s_mov_b32 m0, s34
	s_nop 0
	buffer_load_dwordx4 v141, s[44:47], s71 offen lds
	s_waitcnt vmcnt(6)
	s_barrier
	s_setprio 1
	s_nop 0
	v_mfma_f32_16x16x32_bf16 v[30:33], v[226:229], v[158:161], v[30:33]
	v_mfma_f32_16x16x32_bf16 v[26:29], v[234:237], v[158:161], v[26:29]
	v_mfma_f32_16x16x32_bf16 v[22:25], v[226:229], v[166:169], v[22:25]
	v_mfma_f32_16x16x32_bf16 v[18:21], v[234:237], v[166:169], v[18:21]
	v_mfma_f32_16x16x32_bf16 v[12:15], v[226:229], v[178:181], v[12:15]
	v_mfma_f32_16x16x32_bf16 v[8:11], v[234:237], v[178:181], v[8:11]
	v_mfma_f32_16x16x32_bf16 v[4:7], v[226:229], v[218:221], v[4:7]
	v_mfma_f32_16x16x32_bf16 v[0:3], v[234:237], v[218:221], v[0:3]
	v_mfma_f32_16x16x32_bf16 v[30:33], v[230:233], v[162:165], v[30:33]
	v_mfma_f32_16x16x32_bf16 v[26:29], v[238:241], v[162:165], v[26:29]
	v_mfma_f32_16x16x32_bf16 v[22:25], v[230:233], v[170:173], v[22:25]
	v_mfma_f32_16x16x32_bf16 v[18:21], v[238:241], v[170:173], v[18:21]
	v_mfma_f32_16x16x32_bf16 v[12:15], v[230:233], v[214:217], v[12:15]
	v_mfma_f32_16x16x32_bf16 v[8:11], v[238:241], v[214:217], v[8:11]
	v_mfma_f32_16x16x32_bf16 v[4:7], v[230:233], v[222:225], v[4:7]
	v_mfma_f32_16x16x32_bf16 v[0:3], v[238:241], v[222:225], v[0:3]
	s_setprio 0
	s_barrier
	ds_read_b128 v[132:135], v148
	ds_read_b128 v[136:139], v148 offset:1024
	ds_read_b128 v[150:153], v148 offset:2048
	ds_read_b128 v[154:157], v148 offset:3072
	s_add_i32 s71, s69, 0x80100
	s_mov_b32 m0, s35
	ds_read_b128 v[158:161], v143 offset:32768
	ds_read_b128 v[162:165], v143 offset:33792
	ds_read_b128 v[166:169], v144 offset:32768
	ds_read_b128 v[170:173], v144 offset:33792
	ds_read_b128 v[178:181], v145 offset:32768
	ds_read_b128 v[214:217], v145 offset:33792
	ds_read_b128 v[218:221], v146 offset:32768
	ds_read_b128 v[222:225], v146 offset:33792
	buffer_load_dwordx4 v140, s[48:51], s71 offen lds
	s_mov_b32 m0, s36
	s_nop 0
	buffer_load_dwordx4 v141, s[48:51], s71 offen lds
	s_waitcnt lgkmcnt(8)
	s_barrier
	s_waitcnt lgkmcnt(0)
	s_setprio 1
	s_waitcnt lgkmcnt(0)
	v_mfma_f32_16x16x32_bf16 v[126:129], v[132:135], v[158:161], v[126:129]
	v_mfma_f32_16x16x32_bf16 v[122:125], v[150:153], v[158:161], v[122:125]
	v_mfma_f32_16x16x32_bf16 v[118:121], v[132:135], v[166:169], v[118:121]
	v_mfma_f32_16x16x32_bf16 v[114:117], v[150:153], v[166:169], v[114:117]
	v_mfma_f32_16x16x32_bf16 v[110:113], v[132:135], v[178:181], v[110:113]
	v_mfma_f32_16x16x32_bf16 v[106:109], v[150:153], v[178:181], v[106:109]
	v_mfma_f32_16x16x32_bf16 v[102:105], v[132:135], v[218:221], v[102:105]
	v_mfma_f32_16x16x32_bf16 v[98:101], v[150:153], v[218:221], v[98:101]
	v_mfma_f32_16x16x32_bf16 v[126:129], v[136:139], v[162:165], v[126:129]
	v_mfma_f32_16x16x32_bf16 v[122:125], v[154:157], v[162:165], v[122:125]
	v_mfma_f32_16x16x32_bf16 v[118:121], v[136:139], v[170:173], v[118:121]
	v_mfma_f32_16x16x32_bf16 v[114:117], v[154:157], v[170:173], v[114:117]
	v_mfma_f32_16x16x32_bf16 v[110:113], v[136:139], v[214:217], v[110:113]
	v_mfma_f32_16x16x32_bf16 v[106:109], v[154:157], v[214:217], v[106:109]
	v_mfma_f32_16x16x32_bf16 v[102:105], v[136:139], v[222:225], v[102:105]
	v_mfma_f32_16x16x32_bf16 v[98:101], v[154:157], v[222:225], v[98:101]
	s_setprio 0
	s_barrier
	s_add_i32 s71, s70, 0x180
	s_mov_b32 m0, s37
	ds_read_b128 v[226:229], v149
	ds_read_b128 v[230:233], v149 offset:1024
	ds_read_b128 v[234:237], v149 offset:2048
	ds_read_b128 v[238:241], v149 offset:3072
	buffer_load_dwordx4 v140, s[44:47], s71 offen lds
	s_mov_b32 m0, s38
	s_nop 0
	buffer_load_dwordx4 v141, s[44:47], s71 offen lds
	s_barrier
	s_waitcnt lgkmcnt(0)
	s_setprio 1
	s_waitcnt lgkmcnt(0)
	s_nop 0
	v_mfma_f32_16x16x32_bf16 v[94:97], v[226:229], v[158:161], v[94:97]
	v_mfma_f32_16x16x32_bf16 v[90:93], v[234:237], v[158:161], v[90:93]
	v_mfma_f32_16x16x32_bf16 v[86:89], v[226:229], v[166:169], v[86:89]
	v_mfma_f32_16x16x32_bf16 v[82:85], v[234:237], v[166:169], v[82:85]
	v_mfma_f32_16x16x32_bf16 v[78:81], v[226:229], v[178:181], v[78:81]
	v_mfma_f32_16x16x32_bf16 v[74:77], v[234:237], v[178:181], v[74:77]
	v_mfma_f32_16x16x32_bf16 v[70:73], v[226:229], v[218:221], v[70:73]
	v_mfma_f32_16x16x32_bf16 v[66:69], v[234:237], v[218:221], v[66:69]
	v_mfma_f32_16x16x32_bf16 v[94:97], v[230:233], v[162:165], v[94:97]
	v_mfma_f32_16x16x32_bf16 v[90:93], v[238:241], v[162:165], v[90:93]
	v_mfma_f32_16x16x32_bf16 v[86:89], v[230:233], v[170:173], v[86:89]
	v_mfma_f32_16x16x32_bf16 v[82:85], v[238:241], v[170:173], v[82:85]
	v_mfma_f32_16x16x32_bf16 v[78:81], v[230:233], v[214:217], v[78:81]
	v_mfma_f32_16x16x32_bf16 v[74:77], v[238:241], v[214:217], v[74:77]
	v_mfma_f32_16x16x32_bf16 v[70:73], v[230:233], v[222:225], v[70:73]
	v_mfma_f32_16x16x32_bf16 v[66:69], v[238:241], v[222:225], v[66:69]
	s_setprio 0
	s_addk_i32 s69, 0x180
	s_mov_b32 m0, s39
	s_barrier
	ds_read_b128 v[158:161], v143 offset:49152
	ds_read_b128 v[162:165], v143 offset:50176
	ds_read_b128 v[166:169], v144 offset:49152
	ds_read_b128 v[170:173], v144 offset:50176
	ds_read_b128 v[178:181], v145 offset:49152
	ds_read_b128 v[214:217], v145 offset:50176
	ds_read_b128 v[218:221], v146 offset:49152
	ds_read_b128 v[222:225], v146 offset:50176
	buffer_load_dwordx4 v140, s[48:51], s69 offen lds
	s_mov_b32 m0, s62
	s_nop 0
	buffer_load_dwordx4 v141, s[48:51], s69 offen lds
	s_barrier
	s_waitcnt lgkmcnt(0)
	s_setprio 1
	s_waitcnt lgkmcnt(0)
	v_mfma_f32_16x16x32_bf16 v[62:65], v[132:135], v[158:161], v[62:65]
	v_mfma_f32_16x16x32_bf16 v[58:61], v[150:153], v[158:161], v[58:61]
	v_mfma_f32_16x16x32_bf16 v[54:57], v[132:135], v[166:169], v[54:57]
	v_mfma_f32_16x16x32_bf16 v[50:53], v[150:153], v[166:169], v[50:53]
	v_mfma_f32_16x16x32_bf16 v[46:49], v[132:135], v[178:181], v[46:49]
	v_mfma_f32_16x16x32_bf16 v[42:45], v[150:153], v[178:181], v[42:45]
	v_mfma_f32_16x16x32_bf16 v[38:41], v[132:135], v[218:221], v[38:41]
	v_mfma_f32_16x16x32_bf16 v[34:37], v[150:153], v[218:221], v[34:37]
	v_mfma_f32_16x16x32_bf16 v[62:65], v[136:139], v[162:165], v[62:65]
	v_mfma_f32_16x16x32_bf16 v[58:61], v[154:157], v[162:165], v[58:61]
	v_mfma_f32_16x16x32_bf16 v[54:57], v[136:139], v[170:173], v[54:57]
	v_mfma_f32_16x16x32_bf16 v[50:53], v[154:157], v[170:173], v[50:53]
	v_mfma_f32_16x16x32_bf16 v[46:49], v[136:139], v[214:217], v[46:49]
	v_mfma_f32_16x16x32_bf16 v[42:45], v[154:157], v[214:217], v[42:45]
	v_mfma_f32_16x16x32_bf16 v[38:41], v[136:139], v[222:225], v[38:41]
	v_mfma_f32_16x16x32_bf16 v[34:37], v[154:157], v[222:225], v[34:37]
	s_setprio 0
	s_barrier
	s_add_i32 s70, s70, 0x80180
	s_mov_b32 m0, s63
	s_nop 0
	buffer_load_dwordx4 v140, s[44:47], s70 offen lds
	s_mov_b32 m0, s66
	s_nop 0
	buffer_load_dwordx4 v141, s[44:47], s70 offen lds
	s_waitcnt vmcnt(6)
	s_barrier
	s_setprio 1
	s_nop 0
	v_mfma_f32_16x16x32_bf16 v[30:33], v[226:229], v[158:161], v[30:33]
	v_mfma_f32_16x16x32_bf16 v[26:29], v[234:237], v[158:161], v[26:29]
	v_mfma_f32_16x16x32_bf16 v[22:25], v[226:229], v[166:169], v[22:25]
	v_mfma_f32_16x16x32_bf16 v[18:21], v[234:237], v[166:169], v[18:21]
	v_mfma_f32_16x16x32_bf16 v[12:15], v[226:229], v[178:181], v[12:15]
	v_mfma_f32_16x16x32_bf16 v[8:11], v[234:237], v[178:181], v[8:11]
	v_mfma_f32_16x16x32_bf16 v[4:7], v[226:229], v[218:221], v[4:7]
	v_mfma_f32_16x16x32_bf16 v[0:3], v[234:237], v[218:221], v[0:3]
	v_mfma_f32_16x16x32_bf16 v[30:33], v[230:233], v[162:165], v[30:33]
	v_mfma_f32_16x16x32_bf16 v[26:29], v[238:241], v[162:165], v[26:29]
	v_mfma_f32_16x16x32_bf16 v[22:25], v[230:233], v[170:173], v[22:25]
	v_mfma_f32_16x16x32_bf16 v[18:21], v[238:241], v[170:173], v[18:21]
	v_mfma_f32_16x16x32_bf16 v[12:15], v[230:233], v[214:217], v[12:15]
	v_mfma_f32_16x16x32_bf16 v[8:11], v[238:241], v[214:217], v[8:11]
	v_mfma_f32_16x16x32_bf16 v[4:7], v[230:233], v[222:225], v[4:7]
	v_mfma_f32_16x16x32_bf16 v[0:3], v[238:241], v[222:225], v[0:3]
	s_setprio 0
	s_add_i32 s67, s67, 2
	s_addk_i32 s68, 0x100
	s_cmp_lt_u32 s67, 28
	s_barrier
	s_cbranch_scc1 .LBB0_225
	v_mov_b32_e32 v150, v130
	s_or_b32 s8, s8, 0x80f80
	v_and_b32_e32 v158, 15, v150
	v_bfe_u32 v132, v150, 4, 2
	v_lshlrev_b32_e32 v134, 2, v150
	v_bfe_u32 v152, v150, 6, 2
	v_lshlrev_b32_e32 v151, 4, v132
	v_lshlrev_b32_e32 v133, 6, v158
	v_and_b32_e32 v139, 32, v134
	v_lshlrev_b32_e32 v138, 12, v152
	v_bitop3_b32 v153, v151, v139, v133 bitop3:0x36
	v_add3_u32 v133, s78, v153, v138
	ds_read_b128 v[134:137], v133
	ds_read_b128 v[154:157], v133 offset:1024
	ds_read_b128 v[160:163], v133 offset:2048
	ds_read_b128 v[164:167], v133 offset:3072
	v_ashrrev_i32_e32 v133, 2, v150
	v_lshlrev_b32_e32 v172, 6, v150
	v_and_b32_e32 v133, 0xffffffc0, v133
	v_and_b32_e32 v172, 0x3c0, v172
	v_lshlrev_b32_e32 v159, 7, v133
	v_bitop3_b32 v139, v172, v139, v151 bitop3:0x36
	s_waitcnt vmcnt(0)
	v_add3_u32 v176, 0, v153, v159
	v_add3_u32 v139, 0, v139, v159
	s_mov_b32 m0, s7
	ds_read_b128 v[168:171], v176
	ds_read_b128 v[178:181], v176 offset:1024
	ds_read_b128 v[214:217], v139 offset:2048
	ds_read_b128 v[218:221], v139 offset:3072
	ds_read_b128 v[222:225], v139 offset:4096
	ds_read_b128 v[226:229], v139 offset:5120
	ds_read_b128 v[230:233], v139 offset:6144
	ds_read_b128 v[234:237], v139 offset:7168
	buffer_load_dwordx4 v140, s[48:51], s8 offen lds
	s_mov_b32 m0, s6
	s_nop 0
	buffer_load_dwordx4 v141, s[48:51], s8 offen lds
	s_barrier
	s_waitcnt lgkmcnt(0)
	s_setprio 1
	s_waitcnt lgkmcnt(0)
	v_mfma_f32_16x16x32_bf16 v[126:129], v[134:137], v[168:171], v[126:129]
	v_mfma_f32_16x16x32_bf16 v[122:125], v[160:163], v[168:171], v[122:125]
	v_mfma_f32_16x16x32_bf16 v[118:121], v[134:137], v[214:217], v[118:121]
	v_mfma_f32_16x16x32_bf16 v[114:117], v[160:163], v[214:217], v[114:117]
	v_mfma_f32_16x16x32_bf16 v[110:113], v[134:137], v[222:225], v[110:113]
	v_mfma_f32_16x16x32_bf16 v[106:109], v[160:163], v[222:225], v[106:109]
	v_mfma_f32_16x16x32_bf16 v[102:105], v[134:137], v[230:233], v[102:105]
	v_mfma_f32_16x16x32_bf16 v[98:101], v[160:163], v[230:233], v[98:101]
	v_mfma_f32_16x16x32_bf16 v[126:129], v[154:157], v[178:181], v[126:129]
	v_mfma_f32_16x16x32_bf16 v[122:125], v[164:167], v[178:181], v[122:125]
	v_mfma_f32_16x16x32_bf16 v[118:121], v[154:157], v[218:221], v[118:121]
	v_mfma_f32_16x16x32_bf16 v[114:117], v[164:167], v[218:221], v[114:117]
	v_mfma_f32_16x16x32_bf16 v[110:113], v[154:157], v[226:229], v[110:113]
	v_mfma_f32_16x16x32_bf16 v[106:109], v[164:167], v[226:229], v[106:109]
	v_mfma_f32_16x16x32_bf16 v[102:105], v[154:157], v[234:237], v[102:105]
	v_mfma_f32_16x16x32_bf16 v[98:101], v[164:167], v[234:237], v[98:101]
	s_setprio 0
	v_add3_u32 v159, s77, v153, v138
	s_barrier
	ds_read_b128 v[238:241], v159
	ds_read_b128 v[242:245], v159 offset:1024
	ds_read_b128 v[246:249], v159 offset:2048
	ds_read_b128 v[250:253], v159 offset:3072
	s_barrier
	s_waitcnt lgkmcnt(0)
	s_setprio 1
	s_waitcnt lgkmcnt(0)
	v_mfma_f32_16x16x32_bf16 v[94:97], v[238:241], v[168:171], v[94:97]
	v_mfma_f32_16x16x32_bf16 v[182:185], v[242:245], v[178:181], v[94:97]
	v_mfma_f32_16x16x32_bf16 v[90:93], v[246:249], v[168:171], v[90:93]
	v_mfma_f32_16x16x32_bf16 v[86:89], v[238:241], v[214:217], v[86:89]
	v_mfma_f32_16x16x32_bf16 v[82:85], v[246:249], v[214:217], v[82:85]
	v_mfma_f32_16x16x32_bf16 v[78:81], v[238:241], v[222:225], v[78:81]
	v_mfma_f32_16x16x32_bf16 v[74:77], v[246:249], v[222:225], v[74:77]
	v_mfma_f32_16x16x32_bf16 v[70:73], v[238:241], v[230:233], v[70:73]
	v_mfma_f32_16x16x32_bf16 v[66:69], v[246:249], v[230:233], v[66:69]
	v_mfma_f32_16x16x32_bf16 v[168:171], v[250:253], v[178:181], v[90:93]
	v_mfma_f32_16x16x32_bf16 v[178:181], v[242:245], v[218:221], v[86:89]
	v_mfma_f32_16x16x32_bf16 v[214:217], v[250:253], v[218:221], v[82:85]
	v_mfma_f32_16x16x32_bf16 v[218:221], v[242:245], v[226:229], v[78:81]
	v_mfma_f32_16x16x32_bf16 v[222:225], v[250:253], v[226:229], v[74:77]
	v_mfma_f32_16x16x32_bf16 v[226:229], v[242:245], v[234:237], v[70:73]
	v_mfma_f32_16x16x32_bf16 v[230:233], v[250:253], v[234:237], v[66:69]
	s_setprio 0
	s_barrier
	s_nop 0
	ds_read_b128 v[66:69], v176 offset:16384
	ds_read_b128 v[70:73], v176 offset:17408
	ds_read_b128 v[74:77], v139 offset:18432
	ds_read_b128 v[78:81], v139 offset:19456
	ds_read_b128 v[82:85], v139 offset:20480
	ds_read_b128 v[86:89], v139 offset:21504
	ds_read_b128 v[90:93], v139 offset:22528
	ds_read_b128 v[94:97], v139 offset:23552
	s_waitcnt vmcnt(4)
	s_barrier
	s_waitcnt lgkmcnt(0)
	s_setprio 1
	s_waitcnt lgkmcnt(0)
	v_mfma_f32_16x16x32_bf16 v[62:65], v[134:137], v[66:69], v[62:65]
	v_mfma_f32_16x16x32_bf16 v[58:61], v[160:163], v[66:69], v[58:61]
	v_mfma_f32_16x16x32_bf16 v[54:57], v[134:137], v[74:77], v[54:57]
	v_mfma_f32_16x16x32_bf16 v[50:53], v[160:163], v[74:77], v[50:53]
	v_mfma_f32_16x16x32_bf16 v[46:49], v[134:137], v[82:85], v[46:49]
	v_mfma_f32_16x16x32_bf16 v[42:45], v[160:163], v[82:85], v[42:45]
	v_mfma_f32_16x16x32_bf16 v[38:41], v[134:137], v[90:93], v[38:41]
	v_mfma_f32_16x16x32_bf16 v[34:37], v[160:163], v[90:93], v[34:37]
	v_mfma_f32_16x16x32_bf16 v[62:65], v[154:157], v[70:73], v[62:65]
	v_mfma_f32_16x16x32_bf16 v[58:61], v[164:167], v[70:73], v[58:61]
	v_mfma_f32_16x16x32_bf16 v[54:57], v[154:157], v[78:81], v[54:57]
	v_mfma_f32_16x16x32_bf16 v[50:53], v[164:167], v[78:81], v[50:53]
	v_mfma_f32_16x16x32_bf16 v[46:49], v[154:157], v[86:89], v[46:49]
	v_mfma_f32_16x16x32_bf16 v[42:45], v[164:167], v[86:89], v[42:45]
	v_mfma_f32_16x16x32_bf16 v[38:41], v[154:157], v[94:97], v[38:41]
	v_mfma_f32_16x16x32_bf16 v[34:37], v[164:167], v[94:97], v[34:37]
	s_setprio 0
	s_setprio 1
	v_mfma_f32_16x16x32_bf16 v[30:33], v[238:241], v[66:69], v[30:33]
	v_mfma_f32_16x16x32_bf16 v[26:29], v[246:249], v[66:69], v[26:29]
	v_mfma_f32_16x16x32_bf16 v[22:25], v[238:241], v[74:77], v[22:25]
	v_mfma_f32_16x16x32_bf16 v[18:21], v[246:249], v[74:77], v[18:21]
	v_mfma_f32_16x16x32_bf16 v[12:15], v[238:241], v[82:85], v[12:15]
	v_mfma_f32_16x16x32_bf16 v[8:11], v[246:249], v[82:85], v[8:11]
	v_mfma_f32_16x16x32_bf16 v[4:7], v[238:241], v[90:93], v[4:7]
	v_mfma_f32_16x16x32_bf16 v[0:3], v[246:249], v[90:93], v[0:3]
	v_mfma_f32_16x16x32_bf16 v[134:137], v[242:245], v[70:73], v[30:33]
	v_mfma_f32_16x16x32_bf16 v[154:157], v[250:253], v[70:73], v[26:29]
	v_mfma_f32_16x16x32_bf16 v[160:163], v[242:245], v[78:81], v[22:25]
	v_mfma_f32_16x16x32_bf16 v[164:167], v[250:253], v[78:81], v[18:21]
	v_mfma_f32_16x16x32_bf16 v[234:237], v[242:245], v[86:89], v[12:15]
	v_mfma_f32_16x16x32_bf16 v[82:85], v[250:253], v[86:89], v[8:11]
	v_mfma_f32_16x16x32_bf16 v[238:241], v[242:245], v[94:97], v[4:7]
	v_mfma_f32_16x16x32_bf16 v[242:245], v[250:253], v[94:97], v[0:3]
	s_setprio 0
	s_nop 1
	v_add3_u32 v0, s2, v153, v138
	s_barrier
	ds_read_b128 v[246:249], v0
	ds_read_b128 v[250:253], v0 offset:1024
	ds_read_b128 v[200:203], v0 offset:2048
	ds_read_b128 v[172:175], v0 offset:3072
	ds_read_b128 v[4:7], v176 offset:32768
	ds_read_b128 v[8:11], v176 offset:33792
	ds_read_b128 v[12:15], v139 offset:34816
	ds_read_b128 v[18:21], v139 offset:35840
	ds_read_b128 v[22:25], v139 offset:36864
	ds_read_b128 v[26:29], v139 offset:37888
	ds_read_b128 v[30:33], v139 offset:38912
	ds_read_b128 v[208:211], v139 offset:39936
	s_waitcnt vmcnt(2)
	s_barrier
	s_waitcnt lgkmcnt(0)
	s_setprio 1
	s_waitcnt lgkmcnt(0)
	v_mfma_f32_16x16x32_bf16 v[0:3], v[246:249], v[4:7], v[126:129]
	v_mfma_f32_16x16x32_bf16 v[126:129], v[250:253], v[8:11], v[0:3]
	v_mfma_f32_16x16x32_bf16 v[0:3], v[200:203], v[4:7], v[122:125]
	v_mfma_f32_16x16x32_bf16 v[122:125], v[172:175], v[8:11], v[0:3]
	v_mfma_f32_16x16x32_bf16 v[0:3], v[246:249], v[12:15], v[118:121]
	v_mfma_f32_16x16x32_bf16 v[90:93], v[250:253], v[18:21], v[0:3]
	v_mfma_f32_16x16x32_bf16 v[0:3], v[200:203], v[12:15], v[114:117]
	v_mfma_f32_16x16x32_bf16 v[94:97], v[172:175], v[18:21], v[0:3]
	v_mfma_f32_16x16x32_bf16 v[0:3], v[246:249], v[22:25], v[110:113]
	v_mfma_f32_16x16x32_bf16 v[74:77], v[250:253], v[26:29], v[0:3]
	v_mfma_f32_16x16x32_bf16 v[0:3], v[200:203], v[22:25], v[106:109]
	v_mfma_f32_16x16x32_bf16 v[86:89], v[172:175], v[26:29], v[0:3]
	v_mfma_f32_16x16x32_bf16 v[0:3], v[246:249], v[30:33], v[102:105]
	v_mfma_f32_16x16x32_bf16 v[196:199], v[250:253], v[208:211], v[0:3]
	v_mfma_f32_16x16x32_bf16 v[0:3], v[200:203], v[30:33], v[98:101]
	v_mfma_f32_16x16x32_bf16 v[78:81], v[172:175], v[208:211], v[0:3]
	s_setprio 0
	v_add3_u32 v70, s91, v153, v138
	s_barrier
	ds_read_b128 v[204:207], v70
	s_nop 2
	ds_read_b128 v[0:3], v70 offset:1024
	ds_read_b128 v[66:69], v70 offset:2048
	ds_read_b128 v[70:73], v70 offset:3072
	s_waitcnt vmcnt(0)
	s_barrier
	s_waitcnt lgkmcnt(0)
	s_setprio 1
	s_waitcnt lgkmcnt(0)
	v_mfma_f32_16x16x32_bf16 v[98:101], v[204:207], v[4:7], v[182:185]
	v_mfma_f32_16x16x32_bf16 v[4:7], v[66:69], v[4:7], v[168:171]
	v_mfma_f32_16x16x32_bf16 v[98:101], v[0:3], v[8:11], v[98:101]
	v_mfma_f32_16x16x32_bf16 v[102:105], v[70:73], v[8:11], v[4:7]
	v_mfma_f32_16x16x32_bf16 v[8:11], v[204:207], v[12:15], v[178:181]
	v_mfma_f32_16x16x32_bf16 v[12:15], v[66:69], v[12:15], v[214:217]
	v_mfma_f32_16x16x32_bf16 v[8:11], v[0:3], v[18:21], v[8:11]
	v_mfma_f32_16x16x32_bf16 v[12:15], v[70:73], v[18:21], v[12:15]
	v_mfma_f32_16x16x32_bf16 v[18:21], v[204:207], v[22:25], v[218:221]
	v_mfma_f32_16x16x32_bf16 v[22:25], v[66:69], v[22:25], v[222:225]
	v_mfma_f32_16x16x32_bf16 v[18:21], v[0:3], v[26:29], v[18:21]
	v_mfma_f32_16x16x32_bf16 v[22:25], v[70:73], v[26:29], v[22:25]
	v_mfma_f32_16x16x32_bf16 v[26:29], v[204:207], v[30:33], v[226:229]
	v_mfma_f32_16x16x32_bf16 v[30:33], v[66:69], v[30:33], v[230:233]
	v_mfma_f32_16x16x32_bf16 v[26:29], v[0:3], v[208:211], v[26:29]
	v_mfma_f32_16x16x32_bf16 v[30:33], v[70:73], v[208:211], v[30:33]
	s_setprio 0
	s_barrier
	ds_read_b128 v[168:171], v176 offset:49152
	ds_read_b128 v[178:181], v176 offset:50176
	ds_read_b128 v[208:211], v139 offset:51200
	ds_read_b128 v[214:217], v139 offset:52224
	ds_read_b128 v[218:221], v139 offset:53248
	ds_read_b128 v[222:225], v139 offset:54272
	ds_read_b128 v[226:229], v139 offset:55296
	ds_read_b128 v[230:233], v139 offset:56320
	s_barrier
	s_waitcnt lgkmcnt(0)
	s_setprio 1
	s_waitcnt lgkmcnt(0)
	v_mfma_f32_16x16x32_bf16 v[62:65], v[246:249], v[168:171], v[62:65]
	v_mfma_f32_16x16x32_bf16 v[58:61], v[200:203], v[168:171], v[58:61]
	v_mfma_f32_16x16x32_bf16 v[54:57], v[246:249], v[208:211], v[54:57]
	v_mfma_f32_16x16x32_bf16 v[50:53], v[200:203], v[208:211], v[50:53]
	v_mfma_f32_16x16x32_bf16 v[46:49], v[246:249], v[218:221], v[46:49]
	v_mfma_f32_16x16x32_bf16 v[42:45], v[200:203], v[218:221], v[42:45]
	v_mfma_f32_16x16x32_bf16 v[38:41], v[246:249], v[226:229], v[38:41]
	v_mfma_f32_16x16x32_bf16 v[34:37], v[200:203], v[226:229], v[34:37]
	v_mfma_f32_16x16x32_bf16 v[4:7], v[250:253], v[178:181], v[62:65]
	v_mfma_f32_16x16x32_bf16 v[182:185], v[172:175], v[178:181], v[58:61]
	v_mfma_f32_16x16x32_bf16 v[114:117], v[250:253], v[214:217], v[54:57]
	v_mfma_f32_16x16x32_bf16 v[118:121], v[172:175], v[214:217], v[50:53]
	v_mfma_f32_16x16x32_bf16 v[106:109], v[250:253], v[222:225], v[46:49]
	v_mfma_f32_16x16x32_bf16 v[110:113], v[172:175], v[222:225], v[42:45]
	v_mfma_f32_16x16x32_bf16 v[246:249], v[250:253], v[230:233], v[38:41]
	v_mfma_f32_16x16x32_bf16 v[250:253], v[172:175], v[230:233], v[34:37]
	s_setprio 0
	s_setprio 1
	v_mfma_f32_16x16x32_bf16 v[34:37], v[204:207], v[168:171], v[134:137]
	v_mfma_f32_16x16x32_bf16 v[42:45], v[204:207], v[208:211], v[160:163]
	v_mfma_f32_16x16x32_bf16 v[50:53], v[204:207], v[218:221], v[234:237]
	v_mfma_f32_16x16x32_bf16 v[58:61], v[204:207], v[226:229], v[238:241]
	v_mfma_f32_16x16x32_bf16 v[34:37], v[0:3], v[178:181], v[34:37]
	v_mfma_f32_16x16x32_bf16 v[38:41], v[66:69], v[168:171], v[154:157]
	v_mfma_f32_16x16x32_bf16 v[42:45], v[0:3], v[214:217], v[42:45]
	v_mfma_f32_16x16x32_bf16 v[46:49], v[66:69], v[208:211], v[164:167]
	v_mfma_f32_16x16x32_bf16 v[50:53], v[0:3], v[222:225], v[50:53]
	v_mfma_f32_16x16x32_bf16 v[54:57], v[66:69], v[218:221], v[82:85]
	v_mfma_f32_16x16x32_bf16 v[58:61], v[0:3], v[230:233], v[58:61]
	v_mfma_f32_16x16x32_bf16 v[0:3], v[66:69], v[226:229], v[242:245]
	v_mfma_f32_16x16x32_bf16 v[38:41], v[70:73], v[178:181], v[38:41]
	v_mfma_f32_16x16x32_bf16 v[46:49], v[70:73], v[214:217], v[46:49]
	v_mfma_f32_16x16x32_bf16 v[54:57], v[70:73], v[222:225], v[54:57]
	v_mfma_f32_16x16x32_bf16 v[62:65], v[70:73], v[230:233], v[0:3]
	s_setprio 0
	s_movk_i32 s0, 0x100
	v_cmp_gt_u32_e32 vcc, s0, v150
	s_barrier
	s_and_saveexec_b64 s[6:7], vcc
	s_cbranch_execz .LBB0_228
	s_barrier

.LBB0_646:
	ds_read_b128 v[144:147], v136
	ds_read_b128 v[148:151], v136 offset:1024
	ds_read_b128 v[152:155], v136 offset:2048
	ds_read_b128 v[156:159], v136 offset:3072
	s_add_i32 s39, s19, s38
	s_add_i32 s61, s39, 0x80080
	s_mov_b32 m0, s13
	ds_read_b128 v[160:163], v137
	ds_read_b128 v[164:167], v137 offset:1024
	ds_read_b128 v[168:171], v138
	ds_read_b128 v[172:175], v138 offset:1024
	ds_read_b128 v[176:179], v139
	ds_read_b128 v[180:183], v139 offset:1024
	ds_read_b128 v[196:199], v140
	ds_read_b128 v[200:203], v140 offset:1024
	buffer_load_dwordx4 v134, s[48:51], s61 offen lds
	s_mov_b32 m0, s12
	s_nop 0
	buffer_load_dwordx4 v135, s[48:51], s61 offen lds
	s_waitcnt lgkmcnt(8)
	s_barrier
	s_waitcnt lgkmcnt(0)
	s_setprio 1
	s_waitcnt lgkmcnt(0)
	v_mfma_f32_16x16x32_bf16 v[126:129], v[144:147], v[160:163], v[126:129]
	v_mfma_f32_16x16x32_bf16 v[122:125], v[152:155], v[160:163], v[122:125]
	v_mfma_f32_16x16x32_bf16 v[118:121], v[144:147], v[168:171], v[118:121]
	v_mfma_f32_16x16x32_bf16 v[114:117], v[152:155], v[168:171], v[114:117]
	v_mfma_f32_16x16x32_bf16 v[110:113], v[144:147], v[176:179], v[110:113]
	v_mfma_f32_16x16x32_bf16 v[106:109], v[152:155], v[176:179], v[106:109]
	v_mfma_f32_16x16x32_bf16 v[102:105], v[144:147], v[196:199], v[102:105]
	v_mfma_f32_16x16x32_bf16 v[98:101], v[152:155], v[196:199], v[98:101]
	v_mfma_f32_16x16x32_bf16 v[126:129], v[148:151], v[164:167], v[126:129]
	v_mfma_f32_16x16x32_bf16 v[122:125], v[156:159], v[164:167], v[122:125]
	v_mfma_f32_16x16x32_bf16 v[118:121], v[148:151], v[172:175], v[118:121]
	v_mfma_f32_16x16x32_bf16 v[114:117], v[156:159], v[172:175], v[114:117]
	v_mfma_f32_16x16x32_bf16 v[110:113], v[148:151], v[180:183], v[110:113]
	v_mfma_f32_16x16x32_bf16 v[106:109], v[156:159], v[180:183], v[106:109]
	v_mfma_f32_16x16x32_bf16 v[102:105], v[148:151], v[200:203], v[102:105]
	v_mfma_f32_16x16x32_bf16 v[98:101], v[156:159], v[200:203], v[98:101]
	s_setprio 0
	s_barrier
	s_add_i32 s61, s20, s38
	s_add_i32 s62, s61, 0x100
	s_mov_b32 m0, s22
	ds_read_b128 v[204:207], v141
	ds_read_b128 v[208:211], v141 offset:1024
	ds_read_b128 v[214:217], v141 offset:2048
	ds_read_b128 v[218:221], v141 offset:3072
	buffer_load_dwordx4 v134, s[52:55], s62 offen lds
	s_mov_b32 m0, s23
	s_nop 0
	buffer_load_dwordx4 v135, s[52:55], s62 offen lds
	s_barrier
	s_waitcnt lgkmcnt(0)
	s_setprio 1
	s_waitcnt lgkmcnt(0)
	v_mfma_f32_16x16x32_bf16 v[94:97], v[204:207], v[160:163], v[94:97]
	v_mfma_f32_16x16x32_bf16 v[90:93], v[214:217], v[160:163], v[90:93]
	v_mfma_f32_16x16x32_bf16 v[86:89], v[204:207], v[168:171], v[86:89]
	v_mfma_f32_16x16x32_bf16 v[82:85], v[214:217], v[168:171], v[82:85]
	v_mfma_f32_16x16x32_bf16 v[78:81], v[204:207], v[176:179], v[78:81]
	v_mfma_f32_16x16x32_bf16 v[74:77], v[214:217], v[176:179], v[74:77]
	v_mfma_f32_16x16x32_bf16 v[70:73], v[204:207], v[196:199], v[70:73]
	v_mfma_f32_16x16x32_bf16 v[66:69], v[214:217], v[196:199], v[66:69]
	v_mfma_f32_16x16x32_bf16 v[94:97], v[208:211], v[164:167], v[94:97]
	v_mfma_f32_16x16x32_bf16 v[90:93], v[218:221], v[164:167], v[90:93]
	v_mfma_f32_16x16x32_bf16 v[86:89], v[208:211], v[172:175], v[86:89]
	v_mfma_f32_16x16x32_bf16 v[82:85], v[218:221], v[172:175], v[82:85]
	v_mfma_f32_16x16x32_bf16 v[78:81], v[208:211], v[180:183], v[78:81]
	v_mfma_f32_16x16x32_bf16 v[74:77], v[218:221], v[180:183], v[74:77]
	v_mfma_f32_16x16x32_bf16 v[70:73], v[208:211], v[200:203], v[70:73]
	v_mfma_f32_16x16x32_bf16 v[66:69], v[218:221], v[200:203], v[66:69]
	s_setprio 0
	s_add_i32 s62, s39, 0x100
	s_mov_b32 m0, s21
	s_barrier
	ds_read_b128 v[160:163], v137 offset:16384
	ds_read_b128 v[164:167], v137 offset:17408
	ds_read_b128 v[168:171], v138 offset:16384
	ds_read_b128 v[172:175], v138 offset:17408
	ds_read_b128 v[176:179], v139 offset:16384
	ds_read_b128 v[180:183], v139 offset:17408
	ds_read_b128 v[196:199], v140 offset:16384
	ds_read_b128 v[200:203], v140 offset:17408
	buffer_load_dwordx4 v134, s[48:51], s62 offen lds
	s_mov_b32 m0, s24
	s_nop 0
	buffer_load_dwordx4 v135, s[48:51], s62 offen lds
	s_barrier
	s_waitcnt lgkmcnt(0)
	s_setprio 1
	s_waitcnt lgkmcnt(0)
	s_nop 0
	v_mfma_f32_16x16x32_bf16 v[62:65], v[144:147], v[160:163], v[62:65]
	v_mfma_f32_16x16x32_bf16 v[58:61], v[152:155], v[160:163], v[58:61]
	v_mfma_f32_16x16x32_bf16 v[54:57], v[144:147], v[168:171], v[54:57]
	v_mfma_f32_16x16x32_bf16 v[50:53], v[152:155], v[168:171], v[50:53]
	v_mfma_f32_16x16x32_bf16 v[46:49], v[144:147], v[176:179], v[46:49]
	v_mfma_f32_16x16x32_bf16 v[42:45], v[152:155], v[176:179], v[42:45]
	v_mfma_f32_16x16x32_bf16 v[38:41], v[144:147], v[196:199], v[38:41]
	v_mfma_f32_16x16x32_bf16 v[34:37], v[152:155], v[196:199], v[34:37]
	v_mfma_f32_16x16x32_bf16 v[62:65], v[148:151], v[164:167], v[62:65]
	v_mfma_f32_16x16x32_bf16 v[58:61], v[156:159], v[164:167], v[58:61]
	v_mfma_f32_16x16x32_bf16 v[54:57], v[148:151], v[172:175], v[54:57]
	v_mfma_f32_16x16x32_bf16 v[50:53], v[156:159], v[172:175], v[50:53]
	v_mfma_f32_16x16x32_bf16 v[46:49], v[148:151], v[180:183], v[46:49]
	v_mfma_f32_16x16x32_bf16 v[42:45], v[156:159], v[180:183], v[42:45]
	v_mfma_f32_16x16x32_bf16 v[38:41], v[148:151], v[200:203], v[38:41]
	v_mfma_f32_16x16x32_bf16 v[34:37], v[156:159], v[200:203], v[34:37]
	s_setprio 0
	s_barrier
	s_add_i32 s62, s61, 0x80100
	s_mov_b32 m0, s25
	s_nop 0
	buffer_load_dwordx4 v134, s[52:55], s62 offen lds
	s_mov_b32 m0, s26
	s_nop 0
	buffer_load_dwordx4 v135, s[52:55], s62 offen lds
	s_waitcnt vmcnt(6)
	s_barrier
	s_setprio 1
	s_nop 0
	v_mfma_f32_16x16x32_bf16 v[30:33], v[204:207], v[160:163], v[30:33]
	v_mfma_f32_16x16x32_bf16 v[26:29], v[214:217], v[160:163], v[26:29]
	v_mfma_f32_16x16x32_bf16 v[22:25], v[204:207], v[168:171], v[22:25]
	v_mfma_f32_16x16x32_bf16 v[18:21], v[214:217], v[168:171], v[18:21]
	v_mfma_f32_16x16x32_bf16 v[12:15], v[204:207], v[176:179], v[12:15]
	v_mfma_f32_16x16x32_bf16 v[8:11], v[214:217], v[176:179], v[8:11]
	v_mfma_f32_16x16x32_bf16 v[4:7], v[204:207], v[196:199], v[4:7]
	v_mfma_f32_16x16x32_bf16 v[0:3], v[214:217], v[196:199], v[0:3]
	v_mfma_f32_16x16x32_bf16 v[30:33], v[208:211], v[164:167], v[30:33]
	v_mfma_f32_16x16x32_bf16 v[26:29], v[218:221], v[164:167], v[26:29]
	v_mfma_f32_16x16x32_bf16 v[22:25], v[208:211], v[172:175], v[22:25]
	v_mfma_f32_16x16x32_bf16 v[18:21], v[218:221], v[172:175], v[18:21]
	v_mfma_f32_16x16x32_bf16 v[12:15], v[208:211], v[180:183], v[12:15]
	v_mfma_f32_16x16x32_bf16 v[8:11], v[218:221], v[180:183], v[8:11]
	v_mfma_f32_16x16x32_bf16 v[4:7], v[208:211], v[200:203], v[4:7]
	v_mfma_f32_16x16x32_bf16 v[0:3], v[218:221], v[200:203], v[0:3]
	s_setprio 0
	s_barrier
	ds_read_b128 v[144:147], v142
	ds_read_b128 v[148:151], v142 offset:1024
	ds_read_b128 v[152:155], v142 offset:2048
	ds_read_b128 v[156:159], v142 offset:3072
	s_add_i32 s62, s39, 0x80100
	s_mov_b32 m0, s27
	ds_read_b128 v[160:163], v137 offset:32768
	ds_read_b128 v[164:167], v137 offset:33792
	ds_read_b128 v[168:171], v138 offset:32768
	ds_read_b128 v[172:175], v138 offset:33792
	ds_read_b128 v[176:179], v139 offset:32768
	ds_read_b128 v[180:183], v139 offset:33792
	ds_read_b128 v[196:199], v140 offset:32768
	ds_read_b128 v[200:203], v140 offset:33792
	buffer_load_dwordx4 v134, s[48:51], s62 offen lds
	s_mov_b32 m0, s28
	s_nop 0
	buffer_load_dwordx4 v135, s[48:51], s62 offen lds
	s_waitcnt lgkmcnt(8)
	s_barrier
	s_waitcnt lgkmcnt(0)
	s_setprio 1
	s_waitcnt lgkmcnt(0)
	v_mfma_f32_16x16x32_bf16 v[126:129], v[144:147], v[160:163], v[126:129]
	v_mfma_f32_16x16x32_bf16 v[122:125], v[152:155], v[160:163], v[122:125]
	v_mfma_f32_16x16x32_bf16 v[118:121], v[144:147], v[168:171], v[118:121]
	v_mfma_f32_16x16x32_bf16 v[114:117], v[152:155], v[168:171], v[114:117]
	v_mfma_f32_16x16x32_bf16 v[110:113], v[144:147], v[176:179], v[110:113]
	v_mfma_f32_16x16x32_bf16 v[106:109], v[152:155], v[176:179], v[106:109]
	v_mfma_f32_16x16x32_bf16 v[102:105], v[144:147], v[196:199], v[102:105]
	v_mfma_f32_16x16x32_bf16 v[98:101], v[152:155], v[196:199], v[98:101]
	v_mfma_f32_16x16x32_bf16 v[126:129], v[148:151], v[164:167], v[126:129]
	v_mfma_f32_16x16x32_bf16 v[122:125], v[156:159], v[164:167], v[122:125]
	v_mfma_f32_16x16x32_bf16 v[118:121], v[148:151], v[172:175], v[118:121]
	v_mfma_f32_16x16x32_bf16 v[114:117], v[156:159], v[172:175], v[114:117]
	v_mfma_f32_16x16x32_bf16 v[110:113], v[148:151], v[180:183], v[110:113]
	v_mfma_f32_16x16x32_bf16 v[106:109], v[156:159], v[180:183], v[106:109]
	v_mfma_f32_16x16x32_bf16 v[102:105], v[148:151], v[200:203], v[102:105]
	v_mfma_f32_16x16x32_bf16 v[98:101], v[156:159], v[200:203], v[98:101]
	s_setprio 0
	s_barrier
	s_add_i32 s62, s61, 0x180
	s_mov_b32 m0, s29
	ds_read_b128 v[204:207], v143
	ds_read_b128 v[208:211], v143 offset:1024
	ds_read_b128 v[214:217], v143 offset:2048
	ds_read_b128 v[218:221], v143 offset:3072
	buffer_load_dwordx4 v134, s[52:55], s62 offen lds
	s_mov_b32 m0, s30
	s_nop 0
	buffer_load_dwordx4 v135, s[52:55], s62 offen lds
	s_barrier
	s_waitcnt lgkmcnt(0)
	s_setprio 1
	s_waitcnt lgkmcnt(0)
	s_nop 0
	v_mfma_f32_16x16x32_bf16 v[94:97], v[204:207], v[160:163], v[94:97]
	v_mfma_f32_16x16x32_bf16 v[90:93], v[214:217], v[160:163], v[90:93]
	v_mfma_f32_16x16x32_bf16 v[86:89], v[204:207], v[168:171], v[86:89]
	v_mfma_f32_16x16x32_bf16 v[82:85], v[214:217], v[168:171], v[82:85]
	v_mfma_f32_16x16x32_bf16 v[78:81], v[204:207], v[176:179], v[78:81]
	v_mfma_f32_16x16x32_bf16 v[74:77], v[214:217], v[176:179], v[74:77]
	v_mfma_f32_16x16x32_bf16 v[70:73], v[204:207], v[196:199], v[70:73]
	v_mfma_f32_16x16x32_bf16 v[66:69], v[214:217], v[196:199], v[66:69]
	v_mfma_f32_16x16x32_bf16 v[94:97], v[208:211], v[164:167], v[94:97]
	v_mfma_f32_16x16x32_bf16 v[90:93], v[218:221], v[164:167], v[90:93]
	v_mfma_f32_16x16x32_bf16 v[86:89], v[208:211], v[172:175], v[86:89]
	v_mfma_f32_16x16x32_bf16 v[82:85], v[218:221], v[172:175], v[82:85]
	v_mfma_f32_16x16x32_bf16 v[78:81], v[208:211], v[180:183], v[78:81]
	v_mfma_f32_16x16x32_bf16 v[74:77], v[218:221], v[180:183], v[74:77]
	v_mfma_f32_16x16x32_bf16 v[70:73], v[208:211], v[200:203], v[70:73]
	v_mfma_f32_16x16x32_bf16 v[66:69], v[218:221], v[200:203], v[66:69]
	s_setprio 0
	s_addk_i32 s39, 0x180
	s_mov_b32 m0, s31
	s_barrier
	ds_read_b128 v[160:163], v137 offset:49152
	ds_read_b128 v[164:167], v137 offset:50176
	ds_read_b128 v[168:171], v138 offset:49152
	ds_read_b128 v[172:175], v138 offset:50176
	ds_read_b128 v[176:179], v139 offset:49152
	ds_read_b128 v[180:183], v139 offset:50176
	ds_read_b128 v[196:199], v140 offset:49152
	ds_read_b128 v[200:203], v140 offset:50176
	buffer_load_dwordx4 v134, s[48:51], s39 offen lds
	s_mov_b32 m0, s34
	s_nop 0
	buffer_load_dwordx4 v135, s[48:51], s39 offen lds
	s_barrier
	s_waitcnt lgkmcnt(0)
	s_setprio 1
	s_waitcnt lgkmcnt(0)
	v_mfma_f32_16x16x32_bf16 v[62:65], v[144:147], v[160:163], v[62:65]
	v_mfma_f32_16x16x32_bf16 v[58:61], v[152:155], v[160:163], v[58:61]
	v_mfma_f32_16x16x32_bf16 v[54:57], v[144:147], v[168:171], v[54:57]
	v_mfma_f32_16x16x32_bf16 v[50:53], v[152:155], v[168:171], v[50:53]
	v_mfma_f32_16x16x32_bf16 v[46:49], v[144:147], v[176:179], v[46:49]
	v_mfma_f32_16x16x32_bf16 v[42:45], v[152:155], v[176:179], v[42:45]
	v_mfma_f32_16x16x32_bf16 v[38:41], v[144:147], v[196:199], v[38:41]
	v_mfma_f32_16x16x32_bf16 v[34:37], v[152:155], v[196:199], v[34:37]
	v_mfma_f32_16x16x32_bf16 v[62:65], v[148:151], v[164:167], v[62:65]
	v_mfma_f32_16x16x32_bf16 v[58:61], v[156:159], v[164:167], v[58:61]
	v_mfma_f32_16x16x32_bf16 v[54:57], v[148:151], v[172:175], v[54:57]
	v_mfma_f32_16x16x32_bf16 v[50:53], v[156:159], v[172:175], v[50:53]
	v_mfma_f32_16x16x32_bf16 v[46:49], v[148:151], v[180:183], v[46:49]
	v_mfma_f32_16x16x32_bf16 v[42:45], v[156:159], v[180:183], v[42:45]
	v_mfma_f32_16x16x32_bf16 v[38:41], v[148:151], v[200:203], v[38:41]
	v_mfma_f32_16x16x32_bf16 v[34:37], v[156:159], v[200:203], v[34:37]
	s_setprio 0
	s_barrier
	s_add_i32 s61, s61, 0x80180
	s_mov_b32 m0, s35
	s_nop 0
	buffer_load_dwordx4 v134, s[52:55], s61 offen lds
	s_mov_b32 m0, s36
	s_nop 0
	buffer_load_dwordx4 v135, s[52:55], s61 offen lds
	s_waitcnt vmcnt(6)
	s_barrier
	s_setprio 1
	s_nop 0
	v_mfma_f32_16x16x32_bf16 v[30:33], v[204:207], v[160:163], v[30:33]
	v_mfma_f32_16x16x32_bf16 v[26:29], v[214:217], v[160:163], v[26:29]
	v_mfma_f32_16x16x32_bf16 v[22:25], v[204:207], v[168:171], v[22:25]
	v_mfma_f32_16x16x32_bf16 v[18:21], v[214:217], v[168:171], v[18:21]
	v_mfma_f32_16x16x32_bf16 v[12:15], v[204:207], v[176:179], v[12:15]
	v_mfma_f32_16x16x32_bf16 v[8:11], v[214:217], v[176:179], v[8:11]
	v_mfma_f32_16x16x32_bf16 v[4:7], v[204:207], v[196:199], v[4:7]
	v_mfma_f32_16x16x32_bf16 v[0:3], v[214:217], v[196:199], v[0:3]
	v_mfma_f32_16x16x32_bf16 v[30:33], v[208:211], v[164:167], v[30:33]
	v_mfma_f32_16x16x32_bf16 v[26:29], v[218:221], v[164:167], v[26:29]
	v_mfma_f32_16x16x32_bf16 v[22:25], v[208:211], v[172:175], v[22:25]
	v_mfma_f32_16x16x32_bf16 v[18:21], v[218:221], v[172:175], v[18:21]
	v_mfma_f32_16x16x32_bf16 v[12:15], v[208:211], v[180:183], v[12:15]
	v_mfma_f32_16x16x32_bf16 v[8:11], v[218:221], v[180:183], v[8:11]
	v_mfma_f32_16x16x32_bf16 v[4:7], v[208:211], v[200:203], v[4:7]
	v_mfma_f32_16x16x32_bf16 v[0:3], v[218:221], v[200:203], v[0:3]
	s_setprio 0
	s_add_i32 s37, s37, 2
	s_addk_i32 s38, 0x100
	s_cmp_lt_u32 s37, 28
	s_barrier
	s_cbranch_scc1 .LBB0_646
	v_mov_b32_e32 v144, v130
	s_or_b32 s19, s19, 0x80f80
	v_and_b32_e32 v147, 15, v144
	v_bfe_u32 v146, v144, 4, 2
	v_lshlrev_b32_e32 v150, 2, v144
	v_bfe_u32 v145, v144, 6, 2
	v_lshlrev_b32_e32 v174, 4, v146
	v_lshlrev_b32_e32 v148, 6, v147
	v_and_b32_e32 v175, 32, v150
	v_lshlrev_b32_e32 v149, 12, v145
	v_bitop3_b32 v190, v174, v175, v148 bitop3:0x36
	v_add3_u32 v148, s78, v190, v149
	ds_read_b128 v[150:153], v148
	ds_read_b128 v[154:157], v148 offset:1024
	ds_read_b128 v[158:161], v148 offset:2048
	ds_read_b128 v[162:165], v148 offset:3072
	v_ashrrev_i32_e32 v148, 2, v144
	v_lshlrev_b32_e32 v177, 6, v144
	v_and_b32_e32 v148, 0xffffffc0, v148
	v_and_b32_e32 v177, 0x3c0, v177
	v_lshlrev_b32_e32 v176, 7, v148
	v_bitop3_b32 v174, v177, v175, v174 bitop3:0x36
	s_waitcnt vmcnt(0)
	v_add3_u32 v250, 0, v190, v176
	v_add3_u32 v251, 0, v174, v176
	s_mov_b32 m0, s13
	ds_read_b128 v[166:169], v250
	ds_read_b128 v[170:173], v250 offset:1024
	ds_read_b128 v[174:177], v251 offset:2048
	ds_read_b128 v[178:181], v251 offset:3072
	ds_read_b128 v[182:185], v251 offset:4096
	ds_read_b128 v[196:199], v251 offset:5120
	ds_read_b128 v[200:203], v251 offset:6144
	ds_read_b128 v[204:207], v251 offset:7168
	buffer_load_dwordx4 v134, s[48:51], s19 offen lds
	s_mov_b32 m0, s12
	s_nop 0
	buffer_load_dwordx4 v135, s[48:51], s19 offen lds
	s_barrier
	s_waitcnt lgkmcnt(0)
	s_setprio 1
	s_waitcnt lgkmcnt(0)
	v_mfma_f32_16x16x32_bf16 v[126:129], v[150:153], v[166:169], v[126:129]
	v_mfma_f32_16x16x32_bf16 v[122:125], v[158:161], v[166:169], v[122:125]
	v_mfma_f32_16x16x32_bf16 v[118:121], v[150:153], v[174:177], v[118:121]
	v_mfma_f32_16x16x32_bf16 v[114:117], v[158:161], v[174:177], v[114:117]
	v_mfma_f32_16x16x32_bf16 v[102:105], v[150:153], v[200:203], v[102:105]
	v_mfma_f32_16x16x32_bf16 v[98:101], v[158:161], v[200:203], v[98:101]
	v_mfma_f32_16x16x32_bf16 v[126:129], v[154:157], v[170:173], v[126:129]
	v_mfma_f32_16x16x32_bf16 v[122:125], v[162:165], v[170:173], v[122:125]
	v_mfma_f32_16x16x32_bf16 v[118:121], v[154:157], v[178:181], v[118:121]
	v_mfma_f32_16x16x32_bf16 v[114:117], v[162:165], v[178:181], v[114:117]
	v_mfma_f32_16x16x32_bf16 v[110:113], v[150:153], v[182:185], v[110:113]
	v_mfma_f32_16x16x32_bf16 v[106:109], v[158:161], v[182:185], v[106:109]
	v_mfma_f32_16x16x32_bf16 v[102:105], v[154:157], v[204:207], v[102:105]
	v_mfma_f32_16x16x32_bf16 v[98:101], v[162:165], v[204:207], v[98:101]
	v_mfma_f32_16x16x32_bf16 v[208:211], v[154:157], v[196:199], v[110:113]
	v_mfma_f32_16x16x32_bf16 v[214:217], v[162:165], v[196:199], v[106:109]
	s_setprio 0
	v_add3_u32 v222, s77, v190, v149
	s_barrier
	s_nop 0
	ds_read_b128 v[106:109], v222
	ds_read_b128 v[110:113], v222 offset:1024
	ds_read_b128 v[218:221], v222 offset:2048
	ds_read_b128 v[222:225], v222 offset:3072
	s_barrier
	s_waitcnt lgkmcnt(0)
	s_setprio 1
	s_waitcnt lgkmcnt(0)
	s_nop 0
	v_mfma_f32_16x16x32_bf16 v[94:97], v[106:109], v[166:169], v[94:97]
	v_mfma_f32_16x16x32_bf16 v[82:85], v[218:221], v[174:177], v[82:85]
	v_mfma_f32_16x16x32_bf16 v[78:81], v[106:109], v[182:185], v[78:81]
	v_mfma_f32_16x16x32_bf16 v[74:77], v[218:221], v[182:185], v[74:77]
	v_mfma_f32_16x16x32_bf16 v[70:73], v[106:109], v[200:203], v[70:73]
	v_mfma_f32_16x16x32_bf16 v[66:69], v[218:221], v[200:203], v[66:69]
	v_mfma_f32_16x16x32_bf16 v[94:97], v[110:113], v[170:173], v[94:97]
	v_mfma_f32_16x16x32_bf16 v[90:93], v[218:221], v[166:169], v[90:93]
	v_mfma_f32_16x16x32_bf16 v[86:89], v[106:109], v[174:177], v[86:89]
	v_mfma_f32_16x16x32_bf16 v[82:85], v[222:225], v[178:181], v[82:85]
	v_mfma_f32_16x16x32_bf16 v[78:81], v[110:113], v[196:199], v[78:81]
	v_mfma_f32_16x16x32_bf16 v[74:77], v[222:225], v[196:199], v[74:77]
	v_mfma_f32_16x16x32_bf16 v[70:73], v[110:113], v[204:207], v[70:73]
	v_mfma_f32_16x16x32_bf16 v[66:69], v[222:225], v[204:207], v[66:69]
	v_mfma_f32_16x16x32_bf16 v[166:169], v[222:225], v[170:173], v[90:93]
	v_mfma_f32_16x16x32_bf16 v[170:173], v[110:113], v[178:181], v[86:89]
	s_setprio 0
	s_barrier
	s_nop 0
	ds_read_b128 v[86:89], v250 offset:16384
	ds_read_b128 v[90:93], v250 offset:17408
	ds_read_b128 v[174:177], v251 offset:18432
	ds_read_b128 v[178:181], v251 offset:19456
	ds_read_b128 v[182:185], v251 offset:20480
	ds_read_b128 v[196:199], v251 offset:21504
	ds_read_b128 v[200:203], v251 offset:22528
	ds_read_b128 v[204:207], v251 offset:23552
	s_waitcnt vmcnt(4)
	s_barrier
	s_waitcnt lgkmcnt(0)
	s_setprio 1
	s_waitcnt lgkmcnt(0)
	v_mfma_f32_16x16x32_bf16 v[54:57], v[150:153], v[174:177], v[54:57]
	v_mfma_f32_16x16x32_bf16 v[50:53], v[158:161], v[174:177], v[50:53]
	v_mfma_f32_16x16x32_bf16 v[62:65], v[150:153], v[86:89], v[62:65]
	v_mfma_f32_16x16x32_bf16 v[58:61], v[158:161], v[86:89], v[58:61]
	v_mfma_f32_16x16x32_bf16 v[54:57], v[154:157], v[178:181], v[54:57]
	v_mfma_f32_16x16x32_bf16 v[50:53], v[162:165], v[178:181], v[50:53]
	v_mfma_f32_16x16x32_bf16 v[46:49], v[150:153], v[182:185], v[46:49]
	v_mfma_f32_16x16x32_bf16 v[42:45], v[158:161], v[182:185], v[42:45]
	v_mfma_f32_16x16x32_bf16 v[38:41], v[150:153], v[200:203], v[38:41]
	v_mfma_f32_16x16x32_bf16 v[34:37], v[158:161], v[200:203], v[34:37]
	v_mfma_f32_16x16x32_bf16 v[226:229], v[154:157], v[90:93], v[62:65]
	v_mfma_f32_16x16x32_bf16 v[230:233], v[162:165], v[90:93], v[58:61]
	v_mfma_f32_16x16x32_bf16 v[234:237], v[154:157], v[196:199], v[46:49]
	v_mfma_f32_16x16x32_bf16 v[238:241], v[162:165], v[196:199], v[42:45]
	v_mfma_f32_16x16x32_bf16 v[150:153], v[154:157], v[204:207], v[38:41]
	v_mfma_f32_16x16x32_bf16 v[154:157], v[162:165], v[204:207], v[34:37]
	s_setprio 0
	s_setprio 1
	v_mfma_f32_16x16x32_bf16 v[30:33], v[106:109], v[86:89], v[30:33]
	v_mfma_f32_16x16x32_bf16 v[26:29], v[218:221], v[86:89], v[26:29]
	v_mfma_f32_16x16x32_bf16 v[12:15], v[106:109], v[182:185], v[12:15]
	v_mfma_f32_16x16x32_bf16 v[8:11], v[218:221], v[182:185], v[8:11]
	v_mfma_f32_16x16x32_bf16 v[30:33], v[110:113], v[90:93], v[30:33]
	v_mfma_f32_16x16x32_bf16 v[26:29], v[222:225], v[90:93], v[26:29]
	v_mfma_f32_16x16x32_bf16 v[22:25], v[106:109], v[174:177], v[22:25]
	v_mfma_f32_16x16x32_bf16 v[18:21], v[218:221], v[174:177], v[18:21]
	v_mfma_f32_16x16x32_bf16 v[12:15], v[110:113], v[196:199], v[12:15]
	v_mfma_f32_16x16x32_bf16 v[8:11], v[222:225], v[196:199], v[8:11]
	v_mfma_f32_16x16x32_bf16 v[4:7], v[106:109], v[200:203], v[4:7]
	v_mfma_f32_16x16x32_bf16 v[0:3], v[218:221], v[200:203], v[0:3]
	v_mfma_f32_16x16x32_bf16 v[158:161], v[110:113], v[178:181], v[22:25]
	v_mfma_f32_16x16x32_bf16 v[162:165], v[222:225], v[178:181], v[18:21]
	v_mfma_f32_16x16x32_bf16 v[174:177], v[110:113], v[204:207], v[4:7]
	v_mfma_f32_16x16x32_bf16 v[178:181], v[222:225], v[204:207], v[0:3]
	s_nop 0
	s_setprio 0
	v_add3_u32 v18, s2, v190, v149
	s_barrier
	s_nop 0
	ds_read_b128 v[0:3], v18
	ds_read_b128 v[4:7], v18 offset:1024
	ds_read_b128 v[182:185], v18 offset:2048
	ds_read_b128 v[196:199], v18 offset:3072
	ds_read_b128 v[18:21], v250 offset:32768
	ds_read_b128 v[22:25], v250 offset:33792
	ds_read_b128 v[42:45], v251 offset:34816
	ds_read_b128 v[46:49], v251 offset:35840
	ds_read_b128 v[200:203], v251 offset:36864
	ds_read_b128 v[204:207], v251 offset:37888
	ds_read_b128 v[218:221], v251 offset:38912
	ds_read_b128 v[222:225], v251 offset:39936
	s_waitcnt vmcnt(2)
	s_barrier
	s_waitcnt lgkmcnt(0)
	s_setprio 1
	s_waitcnt lgkmcnt(0)
	v_mfma_f32_16x16x32_bf16 v[34:37], v[0:3], v[18:21], v[126:129]
	v_mfma_f32_16x16x32_bf16 v[110:113], v[4:7], v[22:25], v[34:37]
	v_mfma_f32_16x16x32_bf16 v[34:37], v[182:185], v[18:21], v[122:125]
	v_mfma_f32_16x16x32_bf16 v[106:109], v[196:199], v[22:25], v[34:37]
	v_mfma_f32_16x16x32_bf16 v[34:37], v[0:3], v[42:45], v[118:121]
	v_mfma_f32_16x16x32_bf16 v[90:93], v[4:7], v[46:49], v[34:37]
	v_mfma_f32_16x16x32_bf16 v[34:37], v[182:185], v[42:45], v[114:117]
	v_mfma_f32_16x16x32_bf16 v[86:89], v[196:199], v[46:49], v[34:37]
	v_mfma_f32_16x16x32_bf16 v[34:37], v[0:3], v[200:203], v[208:211]
	v_mfma_f32_16x16x32_bf16 v[62:65], v[4:7], v[204:207], v[34:37]
	v_mfma_f32_16x16x32_bf16 v[34:37], v[182:185], v[200:203], v[214:217]
	v_mfma_f32_16x16x32_bf16 v[58:61], v[196:199], v[204:207], v[34:37]
	v_mfma_f32_16x16x32_bf16 v[34:37], v[0:3], v[218:221], v[102:105]
	v_mfma_f32_16x16x32_bf16 v[38:41], v[4:7], v[222:225], v[34:37]
	v_mfma_f32_16x16x32_bf16 v[34:37], v[182:185], v[218:221], v[98:101]
	v_mfma_f32_16x16x32_bf16 v[34:37], v[196:199], v[222:225], v[34:37]
	s_setprio 0
	s_nop 0
	v_add3_u32 v98, s91, v190, v149
	s_barrier
	ds_read_b128 v[208:211], v98
	ds_read_b128 v[214:217], v98 offset:1024
	ds_read_b128 v[242:245], v98 offset:2048
	ds_read_b128 v[246:249], v98 offset:3072
	s_waitcnt vmcnt(0)
	s_barrier
	s_waitcnt lgkmcnt(0)
	s_setprio 1
	s_waitcnt lgkmcnt(0)
	v_mfma_f32_16x16x32_bf16 v[94:97], v[208:211], v[18:21], v[94:97]
	v_mfma_f32_16x16x32_bf16 v[18:21], v[242:245], v[18:21], v[166:169]
	v_mfma_f32_16x16x32_bf16 v[122:125], v[246:249], v[22:25], v[18:21]
	v_mfma_f32_16x16x32_bf16 v[18:21], v[208:211], v[42:45], v[170:173]
	v_mfma_f32_16x16x32_bf16 v[118:121], v[214:217], v[46:49], v[18:21]
	v_mfma_f32_16x16x32_bf16 v[18:21], v[242:245], v[42:45], v[82:85]
	v_mfma_f32_16x16x32_bf16 v[114:117], v[246:249], v[46:49], v[18:21]
	v_mfma_f32_16x16x32_bf16 v[18:21], v[208:211], v[200:203], v[78:81]
	v_mfma_f32_16x16x32_bf16 v[102:105], v[214:217], v[204:207], v[18:21]
	v_mfma_f32_16x16x32_bf16 v[18:21], v[242:245], v[200:203], v[74:77]
	v_mfma_f32_16x16x32_bf16 v[126:129], v[214:217], v[22:25], v[94:97]
	v_mfma_f32_16x16x32_bf16 v[94:97], v[246:249], v[204:207], v[18:21]
	v_mfma_f32_16x16x32_bf16 v[18:21], v[208:211], v[218:221], v[70:73]
	v_mfma_f32_16x16x32_bf16 v[70:73], v[214:217], v[222:225], v[18:21]
	v_mfma_f32_16x16x32_bf16 v[18:21], v[242:245], v[218:221], v[66:69]
	v_mfma_f32_16x16x32_bf16 v[66:69], v[246:249], v[222:225], v[18:21]
	s_setprio 0
	s_barrier
	ds_read_b128 v[82:85], v250 offset:49152
	ds_read_b128 v[166:169], v250 offset:50176
	ds_read_b128 v[170:173], v251 offset:51200
	ds_read_b128 v[200:203], v251 offset:52224
	ds_read_b128 v[204:207], v251 offset:53248
	ds_read_b128 v[218:221], v251 offset:54272
	ds_read_b128 v[222:225], v251 offset:55296
	ds_read_b128 v[250:253], v251 offset:56320
	s_barrier
	s_waitcnt lgkmcnt(0)
	s_setprio 1
	s_waitcnt lgkmcnt(0)
	v_mfma_f32_16x16x32_bf16 v[18:21], v[0:3], v[82:85], v[226:229]
	v_mfma_f32_16x16x32_bf16 v[78:81], v[4:7], v[166:169], v[18:21]
	v_mfma_f32_16x16x32_bf16 v[18:21], v[182:185], v[82:85], v[230:233]
	v_mfma_f32_16x16x32_bf16 v[74:77], v[196:199], v[166:169], v[18:21]
	v_mfma_f32_16x16x32_bf16 v[18:21], v[0:3], v[170:173], v[54:57]
	v_mfma_f32_16x16x32_bf16 v[46:49], v[4:7], v[200:203], v[18:21]
	v_mfma_f32_16x16x32_bf16 v[18:21], v[182:185], v[170:173], v[50:53]
	v_mfma_f32_16x16x32_bf16 v[42:45], v[196:199], v[200:203], v[18:21]
	v_mfma_f32_16x16x32_bf16 v[18:21], v[0:3], v[204:207], v[234:237]
	v_mfma_f32_16x16x32_bf16 v[0:3], v[0:3], v[222:225], v[150:153]
	v_mfma_f32_16x16x32_bf16 v[22:25], v[4:7], v[218:221], v[18:21]
	v_mfma_f32_16x16x32_bf16 v[18:21], v[182:185], v[204:207], v[238:241]
	v_mfma_f32_16x16x32_bf16 v[4:7], v[4:7], v[250:253], v[0:3]
	v_mfma_f32_16x16x32_bf16 v[0:3], v[182:185], v[222:225], v[154:157]
	v_mfma_f32_16x16x32_bf16 v[18:21], v[196:199], v[218:221], v[18:21]
	v_mfma_f32_16x16x32_bf16 v[0:3], v[196:199], v[250:253], v[0:3]
	s_setprio 0
	s_setprio 1
	v_mfma_f32_16x16x32_bf16 v[26:29], v[242:245], v[82:85], v[26:29]
	v_mfma_f32_16x16x32_bf16 v[30:33], v[208:211], v[82:85], v[30:33]
	v_mfma_f32_16x16x32_bf16 v[82:85], v[246:249], v[166:169], v[26:29]
	v_mfma_f32_16x16x32_bf16 v[26:29], v[208:211], v[170:173], v[158:161]
	v_mfma_f32_16x16x32_bf16 v[54:57], v[214:217], v[200:203], v[26:29]
	v_mfma_f32_16x16x32_bf16 v[26:29], v[242:245], v[170:173], v[162:165]
	v_mfma_f32_16x16x32_bf16 v[8:11], v[242:245], v[204:207], v[8:11]
	v_mfma_f32_16x16x32_bf16 v[50:53], v[246:249], v[200:203], v[26:29]
	v_mfma_f32_16x16x32_bf16 v[12:15], v[208:211], v[204:207], v[12:15]
	v_mfma_f32_16x16x32_bf16 v[26:29], v[246:249], v[218:221], v[8:11]
	v_mfma_f32_16x16x32_bf16 v[8:11], v[208:211], v[222:225], v[174:177]
	v_mfma_f32_16x16x32_bf16 v[98:101], v[214:217], v[166:169], v[30:33]
	v_mfma_f32_16x16x32_bf16 v[30:33], v[214:217], v[218:221], v[12:15]
	v_mfma_f32_16x16x32_bf16 v[12:15], v[214:217], v[250:253], v[8:11]
	v_mfma_f32_16x16x32_bf16 v[8:11], v[242:245], v[222:225], v[178:181]
	v_mfma_f32_16x16x32_bf16 v[8:11], v[246:249], v[250:253], v[8:11]
	s_setprio 0
	s_movk_i32 s1, 0x100
	v_cmp_gt_u32_e32 vcc, s1, v144
	s_barrier
	s_and_saveexec_b64 s[12:13], vcc
	s_cbranch_execz .LBB0_649
	s_barrier
